# q/kv up-projection tile order permuted so tiles sharing an A row block run on the same XCD (L2 locality)
# speedup vs baseline: 1.0874x; 1.0056x over previous
.LBB0_803:
	s_mov_b32 s20, s98
	v_readlane_b32 s0, v254, 1
	s_add_i32 s20, s20, s0
	v_readlane_b32 s0, v255, 14
	s_cmp_lt_i32 s20, s0
	v_readlane_b32 s1, v254, 2
	s_cbranch_scc0 .LBB0_949
.LBB0_804:
	s_mov_b32 s98, s20
	s_cmpk_gt_i32 s20, 0x21f
	s_cbranch_scc1 .Lrm_q
	s_cmpk_lt_u32 s20, 0x200
	s_cbranch_scc0 .Lrm_done
	s_and_b32 s0, s20, 7
	s_lshr_b32 s1, s20, 3
	s_and_b32 s99, s1, 0x38
	s_add_u32 s99, s99, s0
	s_and_b32 s1, s1, 7
	s_lshl_b32 s99, s99, 3
	s_or_b32 s20, s99, s1
	s_branch .Lrm_done
.Lrm_q:
	s_sub_u32 s0, s20, 0x220
	s_cmpk_lt_u32 s0, 0x180
	s_cbranch_scc0 .Lrm_done
	s_and_b32 s1, s0, 7
	s_lshr_b32 s0, s0, 3
	s_mul_i32 s99, s0, 43
	s_lshr_b32 s99, s99, 8
	s_mul_i32 s20, s99, 6
	s_sub_u32 s0, s0, s20
	s_lshl_b32 s99, s99, 3
	s_add_u32 s99, s99, s1
	s_mul_i32 s99, s99, 6
	s_add_u32 s99, s99, s0
	s_add_u32 s20, s99, 0x220
